# SB work-queue: next unit index prefetched by atomic during current unit
# baseline (speedup 1.0000x reference)
.LBB0_447:
	s_lshl_b64 s[12:13], s[50:51], 2
	s_waitcnt lgkmcnt(0)
	s_add_u32 s12, s10, s12
	s_addc_u32 s13, s11, s13
	s_add_u32 s56, s12, 0xf100000
	s_addc_u32 s57, s13, 0
	s_add_u32 s68, s10, 0x6200000
	s_addc_u32 s69, s11, 0
	s_add_u32 s70, s10, 0xef00000
	v_cmp_eq_u32_e64 s[8:9], 0, v228
	s_addc_u32 s71, s11, 0
	v_mov_b32_e32 v247, v199
	v_mov_b64_e32 v[200:201], 0x100
	v_mov_b64_e32 v[196:197], 0xff
	s_and_saveexec_b64 s[10:11], s[8:9]
	s_cbranch_execz .Lsbq_pre_done
	v_mov_b32_e32 v146, 1
	global_atomic_add v146, v1, v146, s[56:57] sc0
.Lsbq_pre_done:
	s_or_b64 exec, exec, s[10:11]
	s_branch .LBB0_450

.LBB0_450:
	s_and_saveexec_b64 s[10:11], s[8:9]
	s_cbranch_execz .LBB0_454
	s_waitcnt vmcnt(0)
	v_readfirstlane_b32 s12, v146
	v_mov_b32_e32 v2, s80
	s_nop 0
	v_mov_b32_e32 v0, s12
	ds_write_b32 v2, v0
	v_mov_b32_e32 v146, 1
	global_atomic_add v146, v1, v146, s[56:57] sc0
